# LN1 row loop: gain/bias vectors hoisted out of the pair loop, prefetch wait moved to first consumer (as LN2); stacked on v25
# speedup vs baseline: 1.0377x; 1.0042x over previous
; __device__ __forceinline__ float wave_sum(float v) { return rdlane(dpp_sum63(v), 63); }
; __device__ __forceinline__ void row_ln(f32x4 (&v)[4], const float* g, const float* b, int lane) {
;     float s = 0.f;
; #pragma unroll
;     for (int j = 0; j < 4; ++j) s += (v[j][0] + v[j][1]) + (v[j][2] + v[j][3]);
;     const float mean = wave_sum(s) * (1.f / D); float s2 = 0.f;
; #pragma unroll
;     for (int j = 0; j < 4; ++j) { v[j] = v[j] - mean; s2 += (v[j][0] * v[j][0] + v[j][1] * v[j][1]) + (v[j][2] * v[j][2] + v[j][3] * v[j][3]); }
;     const float rstd = 1.0f / sqrtf(wave_sum(s2) * (1.f / D) + LN_EPS);
; __device__ __forceinline__ void ln1_router_phase(CArgs& A, Frame& F, int L) {
;     ...
;     if (F.tid < 32) F.LW[LW_CNT + F.tid] = 0u;
;     const int rpw = (T + F.G - 1) / F.G, r0 = F.bid * rpw, r1 = (r0 + rpw < T) ? r0 + rpw : T;
;     const float* g = A.in[17] + ((size_t)L * 3 + 0) * D; const float* bb = A.in[18] + ((size_t)L * 3 + 0) * D;
;     const float* b_rg = A.in[20] + L * 4; const float* b_re = A.in[22] + L * 32;
;     bf16* X = WSP(bf16, WS_X); int* asg = WSP(int, WS_ASG); float* gate = WSP(float, WS_GATE);
;     { u32x4 na[2], nb[2]; const int mf = r0 + 2 * F.wave;
;       if (mf < r1) { row_raw(X + (size_t)mf * D, F.lane, na); row_raw(X + (size_t)((mf + 1 < r1) ? mf + 1 : mf) * D, F.lane, nb); }
;       for (int m = mf; m < r1; m += 2 * NW) { const int mb = (m + 1 < r1) ? m + 1 : m; f32x4 va[4], vb[4];
;         row_unpack(na, va); row_unpack(nb, vb);
;         { const int mn = m + 2 * NW; if (mn < r1) { row_raw(X + (size_t)mn * D, F.lane, na); row_raw(X + (size_t)((mn + 1 < r1) ? mn + 1 : mn) * D, F.lane, nb); } }
;         row_ln(va, g, bb, F.lane); row_ln(vb, g, bb, F.lane);
.LBB0_1160:
	v_lshl_add_u32 v3, s15, 6, v100
	v_cmp_gt_i32_e64 s[38:39], 32, v3
	v_lshl_add_u32 v91, v3, 2, 0
	s_and_saveexec_b64 s[2:3], s[38:39]
	v_add_u32_e32 v0, 0x25800, v91
	ds_write_b32 v0, v2
	s_or_b64 exec, exec, s[2:3]
	v_mov_b32_e32 v0, s4
	v_readlane_b32 s2, v253, 50
	s_waitcnt lgkmcnt(0)
	s_add_u32 s6, s0, 0x7680000
	s_addc_u32 s7, s1, 0
	v_mul_lo_u32 v0, s2, v0
	v_add_u32_e32 v1, s2, v0
	s_load_dwordx2 s[4:5], s[10:11], 0xa0
	s_load_dwordx2 s[2:3], s[10:11], 0xb0
	s_lshl_b32 s8, s15, 1
	v_readfirstlane_b32 s16, v0
	v_min_i32_e32 v1, 0x4200, v1
	v_add_u32_e32 v0, s8, v0
	v_cmp_ge_i32_e32 vcc, v0, v1
	s_and_b64 s[12:13], vcc, exec
	v_readfirstlane_b32 s28, v1
	v_readfirstlane_b32 s12, v0
	s_cbranch_scc1 .LBB0_1167
	s_load_dwordx4 s[40:43], s[10:11], 0x88
	s_mul_i32 s17, s14, 0x3000
	s_mul_hi_i32 s13, s14, 0x3000
	v_lshlrev_b32_e32 v4, 3, v100
	v_ashrrev_i32_e32 v5, 31, v4
	s_waitcnt lgkmcnt(0)
	s_add_u32 s10, s42, s17
	s_addc_u32 s11, s43, s13
	s_add_u32 s18, s40, s17
	s_addc_u32 s19, s41, s13
	s_ashr_i32 s13, s12, 31
	s_lshl_b64 s[26:27], s[12:13], 11
	s_add_u32 s26, s6, s26
	s_addc_u32 s27, s7, s27
	s_add_i32 s13, s12, 1
	s_cmp_lt_i32 s13, s28
	s_cselect_b32 s12, s13, s12
	s_ashr_i32 s13, s12, 31
	s_lshl_b64 s[12:13], s[12:13], 11
	s_add_u32 s12, s6, s12
	v_lshlrev_b64 v[6:7], 1, v[4:5]
	s_addc_u32 s13, s7, s13
	v_lshl_add_u64 v[0:1], s[26:27], 0, v[6:7]
	v_lshl_add_u64 v[8:9], s[12:13], 0, v[6:7]
	global_load_dwordx4 v[32:35], v[0:1], off
	global_load_dwordx4 v[28:31], v[0:1], off offset:1024
	global_load_dwordx4 v[20:23], v[8:9], off offset:1024
	global_load_dwordx4 v[24:27], v[8:9], off
	v_lshlrev_b64 v[4:5], 2, v[4:5]
	v_lshl_add_u64 v[52:53], s[6:7], 0, v[6:7]
	v_lshl_add_u64 v[54:55], s[10:11], 0, v[4:5]
	v_lshl_add_u64 v[56:57], s[18:19], 0, v[4:5]
	global_load_dwordx4 v[104:107], v[56:57], off
	global_load_dwordx4 v[108:111], v[56:57], off offset:16
	global_load_dwordx4 v[112:115], v[56:57], off offset:2048
	global_load_dwordx4 v[116:119], v[56:57], off offset:2064
	global_load_dwordx4 v[120:123], v[54:55], off
	global_load_dwordx4 v[124:127], v[54:55], off offset:16
	global_load_dwordx4 v[128:131], v[54:55], off offset:2048
	global_load_dwordx4 v[132:135], v[54:55], off offset:2064
	s_add_i32 s8, s16, s8
	s_add_i32 s8, s8, 17
	s_waitcnt vmcnt(0)
	v_mov_b64_e32 v[8:9], v[32:33]
	v_mov_b64_e32 v[4:5], v[28:29]
	v_mov_b64_e32 v[12:13], v[20:21]
	v_mov_b64_e32 v[16:17], v[24:25]
	v_mov_b64_e32 v[6:7], v[30:31]
	v_mov_b64_e32 v[10:11], v[34:35]
	v_mov_b64_e32 v[14:15], v[22:23]
	v_mov_b64_e32 v[18:19], v[26:27]
	s_branch .LBB0_1165
.LBB0_1164:
	v_lshlrev_b32_e32 v37, 16, v33
	v_lshlrev_b32_e32 v36, 16, v32
	v_and_b32_e32 v39, 0xffff0000, v33
	v_and_b32_e32 v38, 0xffff0000, v32
	v_lshlrev_b32_e32 v68, 16, v20
	v_and_b32_e32 v69, 0xffff0000, v20
	v_lshlrev_b32_e32 v66, 16, v21
	v_and_b32_e32 v67, 0xffff0000, v21
	v_pk_add_f32 v[20:21], v[36:37], v[38:39]
	v_lshlrev_b32_e32 v41, 16, v35
	v_lshlrev_b32_e32 v40, 16, v34
	v_and_b32_e32 v43, 0xffff0000, v35
	v_and_b32_e32 v42, 0xffff0000, v34
	v_add_f32_e32 v20, v20, v21
	v_add_f32_e32 v83, 0, v20
	v_pk_add_f32 v[20:21], v[40:41], v[42:43]
	v_lshlrev_b32_e32 v88, 16, v28
	v_and_b32_e32 v89, 0xffff0000, v28
	v_lshlrev_b32_e32 v86, 16, v29
	v_and_b32_e32 v87, 0xffff0000, v29
	v_pk_add_f32 v[20:21], v[20:21], v[20:21] op_sel_hi:[0,1]
	v_lshlrev_b32_e32 v80, 16, v30
	v_and_b32_e32 v84, 0xffff0000, v30
	v_lshlrev_b32_e32 v78, 16, v31
	v_and_b32_e32 v82, 0xffff0000, v31
	v_add_f32_e32 v81, v88, v89
	v_add_f32_e32 v85, v86, v87
	v_mov_b32_e32 v79, v21
	v_lshlrev_b32_e32 v60, 16, v22
	v_and_b32_e32 v64, 0xffff0000, v22
	v_lshlrev_b32_e32 v58, 16, v23
	v_and_b32_e32 v62, 0xffff0000, v23
	v_pk_add_f32 v[22:23], v[80:81], v[84:85]
	v_pk_add_f32 v[20:21], v[78:79], v[82:83]
	s_sub_i32 s10, s8, 17
	v_pk_add_f32 v[20:21], v[22:23], v[20:21]
	s_add_i32 s11, s8, -16
	v_add_f32_e32 v20, v20, v21
	v_mov_b32_e32 v21, v2
	s_cmp_lt_i32 s11, s28
	v_add_f32_dpp v20, v20, v20 quad_perm:[1,0,3,2] row_mask:0xf bank_mask:0xf bound_ctrl:1
	s_cselect_b32 s10, s11, s10
	v_lshlrev_b32_e32 v76, 16, v24
	v_add_f32_dpp v20, v20, v20 quad_perm:[2,3,0,1] row_mask:0xf bank_mask:0xf bound_ctrl:1
	v_and_b32_e32 v74, 0xffff0000, v24
	v_lshlrev_b32_e32 v77, 16, v25
	v_add_f32_dpp v20, v20, v20 row_half_mirror row_mask:0xf bank_mask:0xf bound_ctrl:1
	v_and_b32_e32 v75, 0xffff0000, v25
	v_lshlrev_b32_e32 v73, 16, v27
	v_add_f32_dpp v20, v20, v20 row_mirror row_mask:0xf bank_mask:0xf bound_ctrl:1
	v_lshlrev_b32_e32 v72, 16, v26
	v_and_b32_e32 v71, 0xffff0000, v27
	v_mov_b32_dpp v21, v20 row_bcast:15 row_mask:0xa bank_mask:0xf
	v_add_f32_e32 v20, v20, v21
	v_mov_b32_e32 v21, v2
	v_and_b32_e32 v70, 0xffff0000, v26
	v_add_f32_e32 v61, v68, v69
	v_mov_b32_dpp v21, v20 row_bcast:31 row_mask:0xc bank_mask:0xf
	v_add_f32_e32 v20, v20, v21
	v_add_f32_e32 v65, v66, v67
	v_readlane_b32 s11, v20, 63
	s_add_i32 s8, s8, 16
	s_nop 0
	v_fmac_f32_e32 v39, s11, v236
	v_fmac_f32_e32 v38, s11, v236
	v_fmac_f32_e32 v37, s11, v236
	v_fmac_f32_e32 v36, s11, v236
	v_mul_f32_e32 v20, v38, v38
	v_mul_f32_e32 v21, v39, v39
	v_fmac_f32_e32 v20, v36, v36
	v_fmac_f32_e32 v21, v37, v37
	v_fmac_f32_e32 v43, s11, v236
	v_fmac_f32_e32 v42, s11, v236
	v_add_f32_e32 v20, v20, v21
	v_fmac_f32_e32 v41, s11, v236
	v_fmac_f32_e32 v40, s11, v236
	v_mul_f32_e32 v21, v42, v42
	v_mul_f32_e32 v22, v43, v43
	v_fmac_f32_e32 v21, v40, v40
	v_fmac_f32_e32 v22, v41, v41
	v_add_f32_e32 v21, v21, v22
	v_fmac_f32_e32 v87, s11, v236
	v_fmac_f32_e32 v89, s11, v236
	v_add_f32_e32 v20, v20, v21
	v_fmac_f32_e32 v86, s11, v236
	v_fmac_f32_e32 v88, s11, v236
	v_mul_f32_e32 v21, v89, v89
; __device__ __forceinline__ float wave_sum(float v) { return rdlane(dpp_sum63(v), 63); }
; __device__ __forceinline__ void row_ln(f32x4 (&v)[4], const float* g, const float* b, int lane) {
;     ...
; #pragma unroll
;     for (int j = 0; j < 4; ++j) s += (v[j][0] + v[j][1]) + (v[j][2] + v[j][3]);
;     const float mean = wave_sum(s) * (1.f / D); float s2 = 0.f;
; #pragma unroll
;     for (int j = 0; j < 4; ++j) { v[j] = v[j] - mean; s2 += (v[j][0] * v[j][0] + v[j][1] * v[j][1]) + (v[j][2] * v[j][2] + v[j][3] * v[j][3]); }
;     const float rstd = 1.0f / sqrtf(wave_sum(s2) * (1.f / D) + LN_EPS);
; #pragma unroll
;     for (int j = 0; j < 4; ++j) { const f32x4 gg = *(const f32x4*)(g + RCOL(lane, j)), bb = *(const f32x4*)(b + RCOL(lane, j)); v[j] = v[j] * rstd * gg + bb; }
	v_mul_f32_e32 v22, v87, v87
	v_fmac_f32_e32 v21, v88, v88
	v_fmac_f32_e32 v22, v86, v86
	v_add_f32_e32 v21, v21, v22
	v_fmac_f32_e32 v82, s11, v236
	v_fmac_f32_e32 v84, s11, v236
	v_add_f32_e32 v20, v21, v20
	v_fmac_f32_e32 v78, s11, v236
	v_fmac_f32_e32 v80, s11, v236
	v_mul_f32_e32 v21, v84, v84
	v_mul_f32_e32 v22, v82, v82
	v_fmac_f32_e32 v21, v80, v80
	v_fmac_f32_e32 v22, v78, v78
	v_add_f32_e32 v21, v21, v22
	v_add_f32_e32 v20, v21, v20
	v_mov_b32_e32 v21, v2
	v_mov_b32_e32 v45, v38
	v_add_f32_dpp v20, v20, v20 quad_perm:[1,0,3,2] row_mask:0xf bank_mask:0xf bound_ctrl:1
	v_mov_b32_e32 v38, v37
	v_mov_b32_e32 v44, v36
	v_add_f32_dpp v20, v20, v20 quad_perm:[2,3,0,1] row_mask:0xf bank_mask:0xf bound_ctrl:1
	v_mov_b32_e32 v79, v82
	v_pk_add_f32 v[82:83], v[76:77], v[74:75]
	v_add_f32_dpp v20, v20, v20 row_half_mirror row_mask:0xf bank_mask:0xf bound_ctrl:1
	v_add_f32_e32 v59, v82, v83
	v_pk_add_f32 v[82:83], v[72:73], v[70:71]
	v_add_f32_dpp v20, v20, v20 row_mirror row_mask:0xf bank_mask:0xf bound_ctrl:1
	v_pk_add_f32 v[82:83], v[82:83], v[82:83] op_sel_hi:[0,1]
	v_add_f32_e32 v63, 0, v59
	v_mov_b32_dpp v21, v20 row_bcast:15 row_mask:0xa bank_mask:0xf
	v_add_f32_e32 v20, v20, v21
	v_mov_b32_e32 v21, v2
	v_mov_b32_e32 v59, v83
	v_mov_b32_e32 v81, v84
	v_mov_b32_dpp v21, v20 row_bcast:31 row_mask:0xc bank_mask:0xf
	v_add_f32_e32 v20, v20, v21
	v_pk_add_f32 v[84:85], v[60:61], v[64:65]
	v_readlane_b32 s11, v20, 63
	v_pk_add_f32 v[82:83], v[58:59], v[62:63]
	v_mov_b32_e32 v61, v2
	v_fma_f32 v20, s11, v237, v252
	v_cmp_gt_f32_e32 vcc, s31, v20
	v_mul_f32_e32 v21, 0x4f800000, v20
	v_pk_add_f32 v[82:83], v[84:85], v[82:83]
	v_cndmask_b32_e32 v20, v20, v21, vcc
	v_sqrt_f32_e32 v21, v20
	v_add_f32_e32 v59, v82, v83
	v_add_u32_e32 v22, -1, v21
	v_fma_f32 v23, -v22, v21, v20
	v_cmp_ge_f32_e64 s[40:41], 0, v23
	v_add_u32_e32 v23, 1, v21
	v_add_f32_dpp v59, v59, v59 quad_perm:[1,0,3,2] row_mask:0xf bank_mask:0xf bound_ctrl:1
	v_cndmask_b32_e64 v22, v21, v22, s[40:41]
	v_fma_f32 v21, -v23, v21, v20
	v_cmp_lt_f32_e64 s[40:41], 0, v21
	v_add_f32_dpp v59, v59, v59 quad_perm:[2,3,0,1] row_mask:0xf bank_mask:0xf bound_ctrl:1
	s_nop 0
	v_cndmask_b32_e64 v21, v22, v23, s[40:41]
	v_mul_f32_e32 v22, 0x37800000, v21
	v_cndmask_b32_e32 v21, v21, v22, vcc
	v_cmp_class_f32_e32 vcc, v20, v234
	v_add_f32_dpp v59, v59, v59 row_half_mirror row_mask:0xf bank_mask:0xf bound_ctrl:1
	s_nop 0
	v_cndmask_b32_e32 v20, v21, v20, vcc
	v_div_scale_f32 v21, s[18:19], v20, v20, 1.0
	v_rcp_f32_e32 v22, v21
	v_add_f32_dpp v59, v59, v59 row_mirror row_mask:0xf bank_mask:0xf bound_ctrl:1
	v_fma_f32 v23, -v21, v22, 1.0
	v_fmac_f32_e32 v22, v23, v22
	v_div_scale_f32 v23, vcc, 1.0, v20, 1.0
	v_mul_f32_e32 v24, v23, v22
	v_fma_f32 v25, -v21, v24, v23
	v_fmac_f32_e32 v24, v25, v22
	v_fma_f32 v21, -v21, v24, v23
	v_div_fmas_f32 v21, v21, v22, v24
	v_div_fixup_f32 v90, v21, v20, 1.0
	v_mov_b64_e32 v[20:21], v[108:109]
	v_mov_b64_e32 v[22:23], v[110:111]
	v_mov_b64_e32 v[28:29], v[104:105]
	v_mov_b64_e32 v[30:31], v[106:107]
	v_mov_b64_e32 v[24:25], v[124:125]
	v_mov_b64_e32 v[26:27], v[126:127]
	v_mov_b64_e32 v[32:33], v[120:121]
	v_mov_b64_e32 v[34:35], v[122:123]
	v_pk_mul_f32 v[36:37], v[38:39], v[90:91] op_sel_hi:[1,0]
	v_pk_mul_f32 v[44:45], v[44:45], v[90:91] op_sel_hi:[1,0]
	v_mov_b32_dpp v61, v59 row_bcast:15 row_mask:0xa bank_mask:0xf
	v_add_f32_e32 v59, v59, v61
	v_mov_b32_e32 v61, v2
	v_pk_mul_f32 v[80:81], v[80:81], v[90:91] op_sel_hi:[1,0]
	v_pk_mul_f32 v[78:79], v[78:79], v[90:91] op_sel_hi:[1,0]
	v_mov_b32_dpp v61, v59 row_bcast:31 row_mask:0xc bank_mask:0xf
	v_add_f32_e32 v59, v59, v61
	v_pk_mul_f32 v[88:89], v[88:89], v[90:91] op_sel_hi:[1,0]
	v_readlane_b32 s11, v59, 63
	v_pk_mul_f32 v[86:87], v[86:87], v[90:91] op_sel_hi:[1,0]
	s_nop 0
	v_pk_fma_f32 v[92:93], v[30:31], v[36:37], v[34:35]
	v_mov_b32_e32 v36, v40
	v_mov_b32_e32 v37, v42
	v_mov_b32_e32 v42, v41
	v_pk_mul_f32 v[36:37], v[36:37], v[90:91] op_sel_hi:[1,0]
	v_pk_mul_f32 v[38:39], v[42:43], v[90:91] op_sel_hi:[1,0]
	v_pk_fma_f32 v[94:95], v[28:29], v[44:45], v[32:33]
	v_pk_fma_f32 v[96:97], v[22:23], v[38:39], v[26:27]
	v_pk_fma_f32 v[98:99], v[20:21], v[36:37], v[24:25]
	v_mov_b64_e32 v[36:37], v[116:117]
	v_mov_b64_e32 v[38:39], v[118:119]
	v_mov_b64_e32 v[44:45], v[112:113]
	v_mov_b64_e32 v[46:47], v[114:115]
	v_mov_b64_e32 v[40:41], v[132:133]
	v_mov_b64_e32 v[42:43], v[134:135]
	v_mov_b64_e32 v[48:49], v[128:129]
	v_mov_b64_e32 v[50:51], v[130:131]
	v_fmac_f32_e32 v75, s11, v236
	v_fmac_f32_e32 v74, s11, v236
	v_fmac_f32_e32 v77, s11, v236
	v_fmac_f32_e32 v76, s11, v236
	v_mul_f32_e32 v59, v74, v74
	v_mul_f32_e32 v61, v75, v75
	v_fmac_f32_e32 v59, v76, v76
	v_fmac_f32_e32 v61, v77, v77
	v_fmac_f32_e32 v71, s11, v236
	v_fmac_f32_e32 v70, s11, v236
	v_add_f32_e32 v59, v59, v61
	v_fmac_f32_e32 v73, s11, v236
	v_fmac_f32_e32 v72, s11, v236
	v_mul_f32_e32 v61, v70, v70
	v_mul_f32_e32 v63, v71, v71
; __device__ __forceinline__ float wave_sum(float v) { return rdlane(dpp_sum63(v), 63); }
; __device__ __forceinline__ void row_ln(f32x4 (&v)[4], const float* g, const float* b, int lane) {
;     float s = 0.f;
; #pragma unroll
;     for (int j = 0; j < 4; ++j) s += (v[j][0] + v[j][1]) + (v[j][2] + v[j][3]);
;     const float mean = wave_sum(s) * (1.f / D); float s2 = 0.f;
; #pragma unroll
;     for (int j = 0; j < 4; ++j) { v[j] = v[j] - mean; s2 += (v[j][0] * v[j][0] + v[j][1] * v[j][1]) + (v[j][2] * v[j][2] + v[j][3] * v[j][3]); }
;     const float rstd = 1.0f / sqrtf(wave_sum(s2) * (1.f / D) + LN_EPS);
; #pragma unroll
;     for (int j = 0; j < 4; ++j) { const f32x4 gg = *(const f32x4*)(g + RCOL(lane, j)), bb = *(const f32x4*)(b + RCOL(lane, j)); v[j] = v[j] * rstd * gg + bb; }
; __device__ __forceinline__ void ln1_router_phase(CArgs& A, Frame& F, int L) {
;     ...
;       for (int m = mf; m < r1; m += 2 * NW) { const int mb = (m + 1 < r1) ? m + 1 : m; f32x4 va[4], vb[4];
;         row_unpack(na, va); row_unpack(nb, vb);
;         { const int mn = m + 2 * NW; if (mn < r1) { row_raw(X + (size_t)mn * D, F.lane, na); row_raw(X + (size_t)((mn + 1 < r1) ? mn + 1 : mn) * D, F.lane, nb); } }
;         row_ln(va, g, bb, F.lane); row_ln(vb, g, bb, F.lane);
;         row_store_bf(X + (size_t)m * D, F.lane, va); row_store_bf(X + (size_t)mb * D, F.lane, vb); } }
	v_fmac_f32_e32 v61, v72, v72
	v_fmac_f32_e32 v63, v73, v73
	v_add_f32_e32 v61, v61, v63
	v_fmac_f32_e32 v67, s11, v236
	v_fmac_f32_e32 v69, s11, v236
	v_add_f32_e32 v59, v59, v61
	v_fmac_f32_e32 v66, s11, v236
	v_fmac_f32_e32 v68, s11, v236
	v_mul_f32_e32 v61, v69, v69
	v_mul_f32_e32 v63, v67, v67
	v_fmac_f32_e32 v61, v68, v68
	v_fmac_f32_e32 v63, v66, v66
	v_add_f32_e32 v61, v61, v63
	v_fmac_f32_e32 v62, s11, v236
	v_fmac_f32_e32 v64, s11, v236
	v_add_f32_e32 v59, v61, v59
	v_fmac_f32_e32 v58, s11, v236
	v_fmac_f32_e32 v60, s11, v236
	v_mul_f32_e32 v61, v64, v64
	v_mul_f32_e32 v63, v62, v62
	v_fmac_f32_e32 v61, v60, v60
	v_fmac_f32_e32 v63, v58, v58
	v_add_f32_e32 v61, v61, v63
	v_add_f32_e32 v59, v61, v59
	v_mov_b32_e32 v61, v2
	v_mov_b32_e32 v84, v76
	v_add_f32_dpp v59, v59, v59 quad_perm:[1,0,3,2] row_mask:0xf bank_mask:0xf bound_ctrl:1
	v_mov_b32_e32 v85, v74
	v_mov_b32_e32 v74, v77
	v_add_f32_dpp v59, v59, v59 quad_perm:[2,3,0,1] row_mask:0xf bank_mask:0xf bound_ctrl:1
	s_nop 0
	v_pk_fma_f32 v[78:79], v[38:39], v[78:79], v[42:43]
	v_add_f32_dpp v59, v59, v59 row_half_mirror row_mask:0xf bank_mask:0xf bound_ctrl:1
	v_pk_fma_f32 v[80:81], v[36:37], v[80:81], v[40:41]
	s_nop 0
	v_pk_fma_f32 v[86:87], v[46:47], v[86:87], v[50:51]
	v_add_f32_dpp v59, v59, v59 row_mirror row_mask:0xf bank_mask:0xf bound_ctrl:1
	v_pk_fma_f32 v[88:89], v[44:45], v[88:89], v[48:49]
	s_nop 0
	v_mov_b32_dpp v61, v59 row_bcast:15 row_mask:0xa bank_mask:0xf
	v_add_f32_e32 v59, v59, v61
	v_mov_b32_e32 v61, v2
	s_nop 1
	v_mov_b32_dpp v61, v59 row_bcast:31 row_mask:0xc bank_mask:0xf
	v_add_f32_e32 v59, v59, v61
	s_nop 0
	v_readlane_b32 s11, v59, 63
	s_nop 1
	v_fma_f32 v59, s11, v237, v252
	v_cmp_gt_f32_e32 vcc, s31, v59
	v_mul_f32_e32 v61, 0x4f800000, v59
	s_ashr_i32 s11, s10, 31
	v_cndmask_b32_e32 v59, v59, v61, vcc
	v_sqrt_f32_e32 v61, v59
	s_lshl_b64 s[10:11], s[10:11], 11
	s_cmp_ge_i32 s12, s28
	v_add_u32_e32 v63, -1, v61
	v_fma_f32 v65, -v63, v61, v59
	v_cmp_ge_f32_e64 s[40:41], 0, v65
	v_add_u32_e32 v65, 1, v61
	s_nop 0
	v_cndmask_b32_e64 v63, v61, v63, s[40:41]
	v_fma_f32 v61, -v65, v61, v59
	v_cmp_lt_f32_e64 s[40:41], 0, v61
	s_nop 1
	v_cndmask_b32_e64 v61, v63, v65, s[40:41]
	v_mul_f32_e32 v63, 0x37800000, v61
	v_cndmask_b32_e32 v61, v61, v63, vcc
	v_cmp_class_f32_e32 vcc, v59, v234
	s_nop 1
	v_cndmask_b32_e32 v59, v61, v59, vcc
	v_div_scale_f32 v61, s[18:19], v59, v59, 1.0
	v_rcp_f32_e32 v63, v61
	s_nop 0
	v_fma_f32 v65, -v61, v63, 1.0
	v_fmac_f32_e32 v63, v65, v63
	v_div_scale_f32 v65, vcc, 1.0, v59, 1.0
	v_mul_f32_e32 v82, v65, v63
	v_fma_f32 v83, -v61, v82, v65
	v_fmac_f32_e32 v82, v83, v63
	v_fma_f32 v61, -v61, v82, v65
	v_div_fmas_f32 v61, v61, v63, v82
	v_div_fixup_f32 v82, v61, v59, 1.0
	v_pk_mul_f32 v[84:85], v[84:85], v[82:83] op_sel_hi:[1,0]
	v_pk_mul_f32 v[74:75], v[74:75], v[82:83] op_sel_hi:[1,0]
	v_pk_fma_f32 v[28:29], v[28:29], v[84:85], v[32:33]
	v_mov_b32_e32 v32, v72
	v_mov_b32_e32 v33, v70
	v_mov_b32_e32 v70, v73
	v_pk_fma_f32 v[30:31], v[30:31], v[74:75], v[34:35]
	v_pk_mul_f32 v[32:33], v[32:33], v[82:83] op_sel_hi:[1,0]
	v_pk_mul_f32 v[34:35], v[70:71], v[82:83] op_sel_hi:[1,0]
	v_pk_fma_f32 v[24:25], v[20:21], v[32:33], v[24:25]
	v_pk_fma_f32 v[26:27], v[22:23], v[34:35], v[26:27]
	v_pk_mul_f32 v[20:21], v[68:69], v[82:83] op_sel_hi:[1,0]
	v_pk_mul_f32 v[22:23], v[66:67], v[82:83] op_sel_hi:[1,0]
	v_mov_b32_e32 v61, v64
	v_mov_b32_e32 v59, v62
	v_pk_fma_f32 v[32:33], v[46:47], v[22:23], v[50:51]
	v_pk_fma_f32 v[34:35], v[44:45], v[20:21], v[48:49]
	v_pk_mul_f32 v[20:21], v[60:61], v[82:83] op_sel_hi:[1,0]
	v_pk_mul_f32 v[22:23], v[58:59], v[82:83] op_sel_hi:[1,0]
	v_pk_fma_f32 v[36:37], v[36:37], v[20:21], v[40:41]
	v_pk_fma_f32 v[38:39], v[38:39], v[22:23], v[42:43]
	v_cvt_pk_bf16_f32 v20, v94, v95
	v_cvt_pk_bf16_f32 v21, v92, v93
	v_cvt_pk_bf16_f32 v22, v98, v99
	v_cvt_pk_bf16_f32 v23, v96, v97
	global_store_dwordx4 v[0:1], v[20:23], off
	v_lshl_add_u64 v[40:41], v[52:53], 0, s[10:11]
	s_nop 0
	v_cvt_pk_bf16_f32 v20, v88, v89
	v_cvt_pk_bf16_f32 v21, v86, v87
	v_cvt_pk_bf16_f32 v22, v80, v81
	v_cvt_pk_bf16_f32 v23, v78, v79
	global_store_dwordx4 v[0:1], v[20:23], off offset:1024
	v_lshl_add_u64 v[0:1], v[0:1], 0, s[22:23]
	s_nop 0
	v_cvt_pk_bf16_f32 v20, v28, v29
	v_cvt_pk_bf16_f32 v21, v30, v31
	v_cvt_pk_bf16_f32 v22, v24, v25
	v_cvt_pk_bf16_f32 v23, v26, v27
	global_store_dwordx4 v[40:41], v[20:23], off
	s_nop 0
	s_nop 0
	v_cvt_pk_bf16_f32 v20, v34, v35
	v_cvt_pk_bf16_f32 v21, v32, v33
	v_cvt_pk_bf16_f32 v22, v36, v37
	v_cvt_pk_bf16_f32 v23, v38, v39
	global_store_dwordx4 v[40:41], v[20:23], off offset:1024
	s_waitcnt vmcnt(4)
	v_mov_b64_e32 v[26:27], v[18:19]
	v_mov_b64_e32 v[30:31], v[6:7]
	v_mov_b64_e32 v[34:35], v[10:11]
	v_mov_b64_e32 v[24:25], v[16:17]
	v_mov_b64_e32 v[22:23], v[14:15]
	v_mov_b64_e32 v[20:21], v[12:13]
	v_mov_b64_e32 v[32:33], v[8:9]
	v_mov_b64_e32 v[28:29], v[4:5]
	s_cbranch_scc1 .LBB0_1167
